# baseline (speedup 1.0000x reference)
; __device__ __forceinline__ unsigned xb_ld(unsigned* p) { return __hip_atomic_load(p, __ATOMIC_RELAXED, __HIP_MEMORY_SCOPE_AGENT); }
; __device__ __forceinline__ unsigned xb_add(unsigned* p, unsigned v) { return __hip_atomic_fetch_add(p, v, __ATOMIC_RELAXED, __HIP_MEMORY_SCOPE_AGENT); }
; #define XB_SPIN(cond, bar) do { unsigned _sp = 0; while (cond) { __builtin_amdgcn_s_sleep(1); \
;     if ((++_sp & 255u) == 0u) { if (xb_ld(&(bar)[XB_TMO])) break; if (_sp > XB_SPIN_CAP) { atomicAdd(&(bar)[XB_TMO], 1u); break; } } } } while (0)
; __device__ __forceinline__ void xcd_barrier(const XcdBarrier& b, unsigned gen) {
;   asm volatile("s_waitcnt vmcnt(0)" ::: "memory");
;   __syncthreads();
;   if (threadIdx.x == 0) {
;     unsigned* bar = b.bar;
;     __builtin_amdgcn_s_waitcnt(0);
;     const unsigned old = xb_add(&bar[XB_XSUB(b.x)], 1u);
;     if (old + 1u == (gen + 1u) * b.nloc) {
;       __builtin_amdgcn_fence(__ATOMIC_RELEASE, "agent");
;       asm volatile("s_waitcnt vmcnt(0)" ::: "memory");
;       const unsigned og = xb_add(&bar[XB_TOP], 1u);
;       const unsigned tg = gen;
;       if (og + 1u == (tg + 1u) * b.nx) xb_add(&bar[XB_TOPGEN], 1u);
;       else XB_SPIN(xb_ld(&bar[XB_TOPGEN]) == tg, bar);
;       __builtin_amdgcn_fence(__ATOMIC_ACQUIRE, "agent");
;       xb_add(&bar[XB_XGEN(b.x)], 1u);
;     } else {
;       XB_SPIN(xb_ld(&bar[XB_XGEN(b.x)]) == gen, bar);
;       __builtin_amdgcn_fence(__ATOMIC_ACQUIRE, "agent");
;     }
.LBB0_1158:
	s_or_b64 exec, exec, s[4:5]
	s_waitcnt vmcnt(0)
	v_readfirstlane_b32 s2, v1
	s_nop 1
	v_add3_u32 v0, s2, v0, 1
	v_readlane_b32 s2, v249, 2
	s_mul_i32 s2, s12, s2
	s_nop 0
	v_cmp_ne_u32_e32 vcc, s2, v0
	s_and_saveexec_b64 s[2:3], vcc
	s_xor_b64 s[2:3], exec, s[2:3]
	s_cbranch_execz .LBB0_1173
	v_readlane_b32 s4, v249, 13
	v_readlane_b32 s5, v249, 14
	s_nop 4
	global_load_dword v0, v172, s[4:5] sc1
	s_waitcnt vmcnt(0)
	v_cmp_ne_u32_e32 vcc, s42, v0
	s_cbranch_vccnz .LBB0_1172
	s_mov_b32 s8, 1
	s_branch .LBB0_1162
